# P8 row pass as a 4-trip loop (2 rows per trip, rows requested two ahead), byte-packed quantisation
# speedup vs baseline: 1.0141x; 1.0141x over previous
; __device__ __forceinline__ void xn2_rows(const bf16* __restrict__ hb, const float* __restrict__ g, bf16* __restrict__ outp, unsigned char* __restrict__ xq, float* __restrict__ xs, int gwave, int nwaves, int lane, int rend) {
;     const __amdgpu_buffer_rsrc_t rsO = __builtin_amdgcn_make_buffer_rsrc((void*)outp, 0, (unsigned)T * D * 2u, 0x00020000), rsQ = __builtin_amdgcn_make_buffer_rsrc((void*)xq, 0, 16u * (unsigned)MiB, 0x00020000);
; #pragma unroll 2
;     for (int row = gwave; row < rend; row += nwaves) {
;         const v4u* xb = (const v4u*)(hb + (size_t)row * D) + lane;
;         float v[2][8]; float ss = 0.f;
; #pragma unroll
;         for (int j = 0; j < 2; ++j) { const v4u w = xb[64 * j]; const unsigned ww[4] = {w.x, w.y, w.z, w.w};
; #pragma unroll
;             for (int e = 0; e < 4; ++e) { v[j][2 * e] = __uint_as_float(ww[e] << 16); v[j][2 * e + 1] = __uint_as_float(ww[e] & 0xffff0000u); ss += v[j][2 * e] * v[j][2 * e] + v[j][2 * e + 1] * v[j][2 * e + 1]; } }
;         ss = wave_sum(ss);
;         const float r = rsqrtf(ss * (1.f / D) + EPS);
;         float y[2][8]; float mx = 0.f;
; #pragma unroll
;         for (int j = 0; j < 2; ++j) { const float4 g0 = ((const float4*)g)[2 * lane + 128 * j], g1 = ((const float4*)g)[2 * lane + 128 * j + 1]; const float gg[8] = {g0.x, g0.y, g0.z, g0.w, g1.x, g1.y, g1.z, g1.w};
; #pragma unroll
;             for (int e = 0; e < 8; ++e) { y[j][e] = v[j][e] * r * gg[e]; mx = fmaxf(mx, fabsf(y[j][e])); }
;             v4u ow; ow.x = pk2(y[j][0], y[j][1]); ow.y = pk2(y[j][2], y[j][3]); ow.z = pk2(y[j][4], y[j][5]); ow.w = pk2(y[j][6], y[j][7]);
;             __builtin_amdgcn_raw_buffer_store_b128(ow, rsO, (int)(((unsigned)row * D + 8u * (unsigned)lane + 512u * j) * 2u), 0, 16); }
;         mx = wave_max_dpp(mx);
;         const float sc = mx > 0.f ? mx * (1.f / 119.f) : 1.f, inv = 1.f / sc;
.LBB0_564:
	s_or_b64 exec, exec, s[10:11]
	s_andn2_b64 vcc, exec, s[20:21]
	s_barrier
	s_cbranch_vccnz .LBB0_569
	global_load_dwordx4 v[2:5], v[20:21], off offset:16
	global_load_dwordx4 v[6:9], v[20:21], off
	global_load_dwordx4 v[10:13], v[20:21], off offset:2064
	global_load_dwordx4 v[14:17], v[20:21], off offset:2048
	s_lshl_b32 s10, s42, 6
	s_lshl_b32 s11, s43, 8
	s_add_i32 s24, s10, s11
	s_add_i32 s24, s24, s95
	s_ashr_i32 s25, s24, 31
	s_lshl_b64 s[10:11], s[24:25], 2
	s_add_u32 s98, s90, s10
	s_addc_u32 s99, s91, s11
	v_lshl_add_u32 v33, s24, 9, v1
	s_lshl_b64 s[24:25], s[24:25], 11
	v_mov_b32_e32 v27, s25
	v_or_b32_e32 v26, s24, v18
	v_lshl_add_u64 v[148:149], s[90:91], 0, v[26:27]
	s_mov_b32 s24, 0xa400000
	s_mov_b32 s25, 0
	s_nop 0
	v_lshl_add_u64 v[148:149], v[148:149], 0, s[24:25]
	v_lshl_add_u64 v[150:151], v[148:149], 0, s[22:23]
	global_load_dwordx4 v[84:87], v[148:149], off
	global_load_dwordx4 v[88:91], v[148:149], off offset:1024
	global_load_dwordx4 v[92:95], v[150:151], off
	global_load_dwordx4 v[96:99], v[150:151], off offset:1024
	s_mov_b32 s46, 0x4b400008
	s_mov_b32 s47, 0x4b400008
	s_mov_b32 s48, 0x0c0c0400
	s_mov_b32 s49, 0x05040100
	s_mov_b32 s45, 0x0f0f0f0f
	s_mov_b32 s100, 0x8000
	s_mov_b32 s101, 0
	s_mov_b32 s32, 0
	v_mov_b32_e32 v55, 0
	v_mov_b32_e32 v61, 0
	v_mov_b32_e32 v210, v26
	v_mov_b32_e32 v211, v33
	s_waitcnt vmcnt(0)
.Lp8_trip:
	s_waitcnt vmcnt(12)
	v_lshlrev_b32_e32 v34, 16, v84
	v_and_b32_e32 v35, 0xffff0000, v84
	v_lshlrev_b32_e32 v36, 16, v85
	v_and_b32_e32 v37, 0xffff0000, v85
	v_lshlrev_b32_e32 v38, 16, v86
	v_and_b32_e32 v39, 0xffff0000, v86
	v_lshlrev_b32_e32 v40, 16, v87
	v_and_b32_e32 v41, 0xffff0000, v87
	v_lshlrev_b32_e32 v42, 16, v88
	v_and_b32_e32 v43, 0xffff0000, v88
	v_lshlrev_b32_e32 v44, 16, v89
	v_and_b32_e32 v45, 0xffff0000, v89
	v_lshlrev_b32_e32 v46, 16, v90
	v_and_b32_e32 v47, 0xffff0000, v90
	v_lshlrev_b32_e32 v48, 16, v91
	v_and_b32_e32 v49, 0xffff0000, v91
	v_lshl_add_u64 v[148:149], v[148:149], 0, s[100:101]
	global_load_dwordx4 v[84:87], v[148:149], off
	global_load_dwordx4 v[88:91], v[148:149], off offset:1024
	v_pk_mul_f32 v[50:51], v[34:35], v[34:35]
	v_pk_fma_f32 v[50:51], v[36:37], v[36:37], v[50:51]
	v_pk_fma_f32 v[50:51], v[38:39], v[38:39], v[50:51]
	v_pk_fma_f32 v[50:51], v[40:41], v[40:41], v[50:51]
	v_pk_fma_f32 v[50:51], v[42:43], v[42:43], v[50:51]
	v_pk_fma_f32 v[50:51], v[44:45], v[44:45], v[50:51]
	v_pk_fma_f32 v[50:51], v[46:47], v[46:47], v[50:51]
	v_pk_fma_f32 v[50:51], v[48:49], v[48:49], v[50:51]
	v_add_f32_e32 v52, v50, v51
	s_nop 1
	v_add_f32_dpp v52, v52, v52 quad_perm:[1,0,3,2] row_mask:0xf bank_mask:0xf bound_ctrl:1
	s_nop 1
	v_add_f32_dpp v52, v52, v52 quad_perm:[2,3,0,1] row_mask:0xf bank_mask:0xf bound_ctrl:1
	s_nop 1
	v_add_f32_dpp v52, v52, v52 row_half_mirror row_mask:0xf bank_mask:0xf bound_ctrl:1
	s_nop 1
	v_add_f32_dpp v52, v52, v52 row_mirror row_mask:0xf bank_mask:0xf bound_ctrl:1
	s_nop 1
	v_readlane_b32 s28, v52, 16
	v_readlane_b32 s29, v52, 48
	v_readlane_b32 s24, v52, 0
	v_readlane_b32 s25, v52, 32
	s_nop 1
	v_mov_b32_e32 v52, s28
	v_mov_b32_e32 v53, s29
	v_pk_add_f32 v[52:53], s[24:25], v[52:53]
	s_nop 0
	v_add_f32_e32 v52, v52, v53
	v_fmamk_f32 v52, v52, 0x3a800000, v29
	v_rsq_f32_e32 v54, v52
	s_nop 0
	v_pk_mul_f32 v[56:57], v[54:55], v[34:35] op_sel_hi:[0,1]
	v_pk_mul_f32 v[164:165], v[6:7], v[56:57]
	v_pk_mul_f32 v[56:57], v[54:55], v[36:37] op_sel_hi:[0,1]
	v_pk_mul_f32 v[166:167], v[8:9], v[56:57]
	v_pk_mul_f32 v[56:57], v[54:55], v[38:39] op_sel_hi:[0,1]
	v_pk_mul_f32 v[168:169], v[2:3], v[56:57]
	v_pk_mul_f32 v[56:57], v[54:55], v[40:41] op_sel_hi:[0,1]
	v_pk_mul_f32 v[170:171], v[4:5], v[56:57]
	v_pk_mul_f32 v[56:57], v[54:55], v[42:43] op_sel_hi:[0,1]
	v_pk_mul_f32 v[172:173], v[14:15], v[56:57]
	v_pk_mul_f32 v[56:57], v[54:55], v[44:45] op_sel_hi:[0,1]
	v_pk_mul_f32 v[174:175], v[16:17], v[56:57]
	v_pk_mul_f32 v[56:57], v[54:55], v[46:47] op_sel_hi:[0,1]
	v_pk_mul_f32 v[176:177], v[10:11], v[56:57]
	v_pk_mul_f32 v[56:57], v[54:55], v[48:49] op_sel_hi:[0,1]
	v_pk_mul_f32 v[178:179], v[12:13], v[56:57]
	v_max3_f32 v58, |v164|, 0, |v165|
	v_max3_f32 v58, v58, |v166|, |v167|
	v_max3_f32 v58, v58, |v168|, |v169|
	v_max3_f32 v58, v58, |v170|, |v171|
	v_max3_f32 v58, v58, |v172|, |v173|
	v_max3_f32 v58, v58, |v174|, |v175|
	v_max3_f32 v58, v58, |v176|, |v177|
	v_max3_f32 v58, v58, |v178|, |v179|
	v_cvt_pk_bf16_f32 v62, v164, v165
	v_cvt_pk_bf16_f32 v63, v166, v167
	v_cvt_pk_bf16_f32 v64, v168, v169
	v_cvt_pk_bf16_f32 v65, v170, v171
	v_cvt_pk_bf16_f32 v66, v172, v173
	v_cvt_pk_bf16_f32 v67, v174, v175
	v_cvt_pk_bf16_f32 v68, v176, v177
	v_cvt_pk_bf16_f32 v69, v178, v179
	buffer_store_dwordx4 v[62:65], v210, s[12:15], 0 offen sc1
	buffer_store_dwordx4 v[66:69], v210, s[12:15], 0 offen offset:1024 sc1
	v_add_u32_e32 v210, 0x4000, v210
	s_nop 1
	v_max_f32_dpp v58, v58, v58 quad_perm:[1,0,3,2] row_mask:0xf bank_mask:0xf
	s_nop 1
	v_max_f32_dpp v58, v58, v58 quad_perm:[2,3,0,1] row_mask:0xf bank_mask:0xf
	s_nop 1
	v_max_f32_dpp v58, v58, v58 row_half_mirror row_mask:0xf bank_mask:0xf
	s_nop 1
	v_max_f32_dpp v58, v58, v58 row_mirror row_mask:0xf bank_mask:0xf
	s_nop 1
	v_readlane_b32 s28, v58, 32
	v_readlane_b32 s29, v58, 48
	v_readlane_b32 s24, v58, 0
	v_readlane_b32 s25, v58, 16
	s_nop 1
	v_mov_b32_e32 v59, s29
	v_max_f32_e32 v59, s28, v59
	v_mov_b32_e32 v70, s25
	v_max3_f32 v59, s24, v70, v59
	v_mul_f32_e32 v70, 0x3c09ae41, v59
	v_cmp_lt_f32_e32 vcc, 0, v59
	s_nop 1
	v_cndmask_b32_e32 v59, 1.0, v70, vcc
	v_div_scale_f32 v70, s[24:25], v59, v59, 1.0
	v_rcp_f32_e32 v71, v70
	v_div_scale_f32 v72, vcc, 1.0, v59, 1.0
; __device__ __forceinline__ void xn2_rows(const bf16* __restrict__ hb, const float* __restrict__ g, bf16* __restrict__ outp, unsigned char* __restrict__ xq, float* __restrict__ xs, int gwave, int nwaves, int lane, int rend) {
;     ...
;         const v4u* xb = (const v4u*)(hb + (size_t)row * D) + lane;
;         float v[2][8]; float ss = 0.f;
; #pragma unroll
;         for (int j = 0; j < 2; ++j) { const v4u w = xb[64 * j]; const unsigned ww[4] = {w.x, w.y, w.z, w.w};
; #pragma unroll
;             for (int e = 0; e < 4; ++e) { v[j][2 * e] = __uint_as_float(ww[e] << 16); v[j][2 * e + 1] = __uint_as_float(ww[e] & 0xffff0000u); ss += v[j][2 * e] * v[j][2 * e] + v[j][2 * e + 1] * v[j][2 * e + 1]; } }
;         ss = wave_sum(ss);
;         const float r = rsqrtf(ss * (1.f / D) + EPS);
;         float y[2][8]; float mx = 0.f;
; #pragma unroll
;         for (int j = 0; j < 2; ++j) { const float4 g0 = ((const float4*)g)[2 * lane + 128 * j], g1 = ((const float4*)g)[2 * lane + 128 * j + 1]; const float gg[8] = {g0.x, g0.y, g0.z, g0.w, g1.x, g1.y, g1.z, g1.w};
; #pragma unroll
;             for (int e = 0; e < 8; ++e) { y[j][e] = v[j][e] * r * gg[e]; mx = fmaxf(mx, fabsf(y[j][e])); }
;             v4u ow; ow.x = pk2(y[j][0], y[j][1]); ow.y = pk2(y[j][2], y[j][3]); ow.z = pk2(y[j][4], y[j][5]); ow.w = pk2(y[j][6], y[j][7]);
;             __builtin_amdgcn_raw_buffer_store_b128(ow, rsO, (int)(((unsigned)row * D + 8u * (unsigned)lane + 512u * j) * 2u), 0, 16); }
;         mx = wave_max_dpp(mx);
;         const float sc = mx > 0.f ? mx * (1.f / 119.f) : 1.f, inv = 1.f / sc;
;         int sx = 0; unsigned W[4];
; #pragma unroll
;         for (int j = 0; j < 2; ++j) { unsigned wh = 0u, wl = 0u;
; #pragma unroll
;             for (int e = 0; e < 8; ++e) { const int q = (int)rintf(y[j][e] * inv); sx += q; const unsigned tq = (unsigned)(q + 8);
;                 wl |= ((tq & 15u) ^ 8u) << (4 * e); wh |= (((unsigned)((int)tq >> 4)) & 15u) << (4 * e); }
;             W[j] = wh; W[2 + j] = wl; }
;         { const bool o1 = (lane & 1) != 0, o2 = (lane & 2) != 0;
; #pragma unroll
;           for (int p = 0; p < 4; p += 2) { const unsigned t = o1 ? W[p] : W[p + 1]; const unsigned rc = (unsigned)__builtin_amdgcn_update_dpp(0, (int)t, 0xB1, 0xf, 0xf, false); if (o1) W[p] = rc; else W[p + 1] = rc; }
; #pragma unroll
	v_fma_f32 v73, -v70, v71, 1.0
	v_fmac_f32_e32 v71, v73, v71
	v_mul_f32_e32 v73, v72, v71
	v_fma_f32 v74, -v70, v73, v72
	v_fmac_f32_e32 v73, v74, v71
	v_fma_f32 v70, -v70, v73, v72
	v_div_fmas_f32 v70, v70, v71, v73
	v_div_fixup_f32 v60, v70, v59, 1.0
	v_pk_mul_f32 v[56:57], v[60:61], v[164:165] op_sel_hi:[0,1]
	v_pk_add_f32 v[180:181], s[46:47], v[56:57]
	v_pk_mul_f32 v[56:57], v[60:61], v[166:167] op_sel_hi:[0,1]
	v_pk_add_f32 v[182:183], s[46:47], v[56:57]
	v_pk_mul_f32 v[56:57], v[60:61], v[168:169] op_sel_hi:[0,1]
	v_pk_add_f32 v[184:185], s[46:47], v[56:57]
	v_pk_mul_f32 v[56:57], v[60:61], v[170:171] op_sel_hi:[0,1]
	v_pk_add_f32 v[186:187], s[46:47], v[56:57]
	v_pk_mul_f32 v[56:57], v[60:61], v[172:173] op_sel_hi:[0,1]
	v_pk_add_f32 v[188:189], s[46:47], v[56:57]
	v_pk_mul_f32 v[56:57], v[60:61], v[174:175] op_sel_hi:[0,1]
	v_pk_add_f32 v[190:191], s[46:47], v[56:57]
	v_pk_mul_f32 v[56:57], v[60:61], v[176:177] op_sel_hi:[0,1]
	v_pk_add_f32 v[192:193], s[46:47], v[56:57]
	v_pk_mul_f32 v[56:57], v[60:61], v[178:179] op_sel_hi:[0,1]
	v_pk_add_f32 v[194:195], s[46:47], v[56:57]
	v_add3_u32 v208, v180, v181, v182
	v_add3_u32 v208, v208, v183, v184
	v_add3_u32 v208, v208, v185, v186
	v_add3_u32 v208, v208, v187, v188
	v_add3_u32 v208, v208, v189, v190
	v_add3_u32 v208, v208, v191, v192
	v_add3_u32 v208, v208, v193, v194
	v_add_u32_e32 v208, v208, v195
	v_add_u32_e32 v208, 0x4bffff80, v208
	v_perm_b32 v204, v182, v180, s48
	v_perm_b32 v205, v186, v184, s48
	v_perm_b32 v196, v205, v204, s49
	v_perm_b32 v204, v183, v181, s48
	v_perm_b32 v205, v187, v185, s48
	v_perm_b32 v197, v205, v204, s49
	v_lshlrev_b32_e32 v204, 4, v197
	v_lshrrev_b32_e32 v205, 4, v196
	v_bfi_b32 v202, s45, v196, v204
	v_bfi_b32 v200, s45, v205, v197
	v_xor_b32_e32 v202, 0x88888888, v202
	v_perm_b32 v204, v190, v188, s48
	v_perm_b32 v205, v194, v192, s48
	v_perm_b32 v196, v205, v204, s49
	v_perm_b32 v204, v191, v189, s48
	v_perm_b32 v205, v195, v193, s48
	v_perm_b32 v197, v205, v204, s49
	v_lshlrev_b32_e32 v204, 4, v197
	v_lshrrev_b32_e32 v205, 4, v196
	v_bfi_b32 v203, s45, v196, v204
	v_bfi_b32 v201, s45, v205, v197
	v_xor_b32_e32 v203, 0x88888888, v203
	v_cndmask_b32_e64 v204, v200, v201, s[4:5]
	v_cndmask_b32_e64 v205, v202, v203, s[4:5]
	s_nop 1
	v_mov_b32_dpp v206, v204 quad_perm:[1,0,3,2] row_mask:0xf bank_mask:0xf
	v_mov_b32_dpp v207, v205 quad_perm:[1,0,3,2] row_mask:0xf bank_mask:0xf
	s_nop 0
	v_cndmask_b32_e64 v200, v206, v200, s[4:5]
	v_cndmask_b32_e64 v201, v201, v206, s[4:5]
	v_cndmask_b32_e64 v202, v207, v202, s[4:5]
	v_cndmask_b32_e64 v203, v203, v207, s[4:5]
	v_cndmask_b32_e64 v204, v200, v202, s[6:7]
	v_cndmask_b32_e64 v205, v201, v203, s[6:7]
	s_nop 1
	v_mov_b32_dpp v206, v204 quad_perm:[2,3,0,1] row_mask:0xf bank_mask:0xf
	v_mov_b32_dpp v207, v205 quad_perm:[2,3,0,1] row_mask:0xf bank_mask:0xf
	s_nop 0
	v_cndmask_b32_e64 v200, v206, v200, s[6:7]
	v_cndmask_b32_e64 v202, v202, v206, s[6:7]
	v_cndmask_b32_e64 v201, v207, v201, s[6:7]
	v_cndmask_b32_e64 v203, v203, v207, s[6:7]
	buffer_store_dwordx4 v[200:203], v211, s[16:19], 0 offen sc1
	v_add_u32_e32 v211, 0x1000, v211
	s_nop 1
	v_add_u32_dpp v208, v208, v208 quad_perm:[1,0,3,2] row_mask:0xf bank_mask:0xf bound_ctrl:1
	s_nop 1
	v_add_u32_dpp v208, v208, v208 quad_perm:[2,3,0,1] row_mask:0xf bank_mask:0xf bound_ctrl:1
	s_nop 1
	v_add_u32_dpp v208, v208, v208 row_half_mirror row_mask:0xf bank_mask:0xf bound_ctrl:1
	s_nop 1
	v_add_u32_dpp v208, v208, v208 row_mirror row_mask:0xf bank_mask:0xf bound_ctrl:1
	s_nop 1
	v_readlane_b32 s28, v208, 0
	v_readlane_b32 s29, v208, 16
	v_readlane_b32 s30, v208, 32
	v_readlane_b32 s31, v208, 48
	s_nop 1
	s_add_i32 s28, s29, s28
	s_add_i32 s28, s28, s30
	s_add_i32 s30, s28, s31
	s_and_saveexec_b64 s[24:25], s[8:9]
	global_store_dword v30, v59, s[98:99] sc1
	v_mov_b32_e32 v70, s30
	global_store_dword v31, v70, s[98:99] sc1
	s_mov_b64 exec, s[24:25]
	s_add_u32 s98, s98, 32
	s_addc_u32 s99, s99, 0
	s_waitcnt vmcnt(12)
	v_lshlrev_b32_e32 v34, 16, v92
	v_and_b32_e32 v35, 0xffff0000, v92
	v_lshlrev_b32_e32 v36, 16, v93
	v_and_b32_e32 v37, 0xffff0000, v93
	v_lshlrev_b32_e32 v38, 16, v94
	v_and_b32_e32 v39, 0xffff0000, v94
	v_lshlrev_b32_e32 v40, 16, v95
	v_and_b32_e32 v41, 0xffff0000, v95
	v_lshlrev_b32_e32 v42, 16, v96
	v_and_b32_e32 v43, 0xffff0000, v96
	v_lshlrev_b32_e32 v44, 16, v97
	v_and_b32_e32 v45, 0xffff0000, v97
	v_lshlrev_b32_e32 v46, 16, v98
	v_and_b32_e32 v47, 0xffff0000, v98
	v_lshlrev_b32_e32 v48, 16, v99
	v_and_b32_e32 v49, 0xffff0000, v99
	v_lshl_add_u64 v[150:151], v[150:151], 0, s[100:101]
	global_load_dwordx4 v[92:95], v[150:151], off
	global_load_dwordx4 v[96:99], v[150:151], off offset:1024
	v_pk_mul_f32 v[50:51], v[34:35], v[34:35]
	v_pk_fma_f32 v[50:51], v[36:37], v[36:37], v[50:51]
	v_pk_fma_f32 v[50:51], v[38:39], v[38:39], v[50:51]
	v_pk_fma_f32 v[50:51], v[40:41], v[40:41], v[50:51]
	v_pk_fma_f32 v[50:51], v[42:43], v[42:43], v[50:51]
	v_pk_fma_f32 v[50:51], v[44:45], v[44:45], v[50:51]
	v_pk_fma_f32 v[50:51], v[46:47], v[46:47], v[50:51]
	v_pk_fma_f32 v[50:51], v[48:49], v[48:49], v[50:51]
	v_add_f32_e32 v52, v50, v51
	s_nop 1
	v_add_f32_dpp v52, v52, v52 quad_perm:[1,0,3,2] row_mask:0xf bank_mask:0xf bound_ctrl:1
	s_nop 1
	v_add_f32_dpp v52, v52, v52 quad_perm:[2,3,0,1] row_mask:0xf bank_mask:0xf bound_ctrl:1
	s_nop 1
	v_add_f32_dpp v52, v52, v52 row_half_mirror row_mask:0xf bank_mask:0xf bound_ctrl:1
	s_nop 1
	v_add_f32_dpp v52, v52, v52 row_mirror row_mask:0xf bank_mask:0xf bound_ctrl:1
	s_nop 1
	v_readlane_b32 s28, v52, 16
	v_readlane_b32 s29, v52, 48
	v_readlane_b32 s24, v52, 0
	v_readlane_b32 s25, v52, 32
	s_nop 1
	v_mov_b32_e32 v52, s28
; __device__ __forceinline__ void xn2_rows(const bf16* __restrict__ hb, const float* __restrict__ g, bf16* __restrict__ outp, unsigned char* __restrict__ xq, float* __restrict__ xs, int gwave, int nwaves, int lane, int rend) {
;     ...
;         const v4u* xb = (const v4u*)(hb + (size_t)row * D) + lane;
;         float v[2][8]; float ss = 0.f;
; #pragma unroll
;         for (int j = 0; j < 2; ++j) { const v4u w = xb[64 * j]; const unsigned ww[4] = {w.x, w.y, w.z, w.w};
; #pragma unroll
;             for (int e = 0; e < 4; ++e) { v[j][2 * e] = __uint_as_float(ww[e] << 16); v[j][2 * e + 1] = __uint_as_float(ww[e] & 0xffff0000u); ss += v[j][2 * e] * v[j][2 * e] + v[j][2 * e + 1] * v[j][2 * e + 1]; } }
;         ss = wave_sum(ss);
;         const float r = rsqrtf(ss * (1.f / D) + EPS);
;         float y[2][8]; float mx = 0.f;
; #pragma unroll
;         for (int j = 0; j < 2; ++j) { const float4 g0 = ((const float4*)g)[2 * lane + 128 * j], g1 = ((const float4*)g)[2 * lane + 128 * j + 1]; const float gg[8] = {g0.x, g0.y, g0.z, g0.w, g1.x, g1.y, g1.z, g1.w};
; #pragma unroll
;             for (int e = 0; e < 8; ++e) { y[j][e] = v[j][e] * r * gg[e]; mx = fmaxf(mx, fabsf(y[j][e])); }
;             v4u ow; ow.x = pk2(y[j][0], y[j][1]); ow.y = pk2(y[j][2], y[j][3]); ow.z = pk2(y[j][4], y[j][5]); ow.w = pk2(y[j][6], y[j][7]);
;             __builtin_amdgcn_raw_buffer_store_b128(ow, rsO, (int)(((unsigned)row * D + 8u * (unsigned)lane + 512u * j) * 2u), 0, 16); }
;         mx = wave_max_dpp(mx);
;         const float sc = mx > 0.f ? mx * (1.f / 119.f) : 1.f, inv = 1.f / sc;
;         int sx = 0; unsigned W[4];
; #pragma unroll
;         for (int j = 0; j < 2; ++j) { unsigned wh = 0u, wl = 0u;
; #pragma unroll
;             for (int e = 0; e < 8; ++e) { const int q = (int)rintf(y[j][e] * inv); sx += q; const unsigned tq = (unsigned)(q + 8);
;                 wl |= ((tq & 15u) ^ 8u) << (4 * e); wh |= (((unsigned)((int)tq >> 4)) & 15u) << (4 * e); }
;             W[j] = wh; W[2 + j] = wl; }
;         { const bool o1 = (lane & 1) != 0, o2 = (lane & 2) != 0;
; #pragma unroll
;           for (int p = 0; p < 4; p += 2) { const unsigned t = o1 ? W[p] : W[p + 1]; const unsigned rc = (unsigned)__builtin_amdgcn_update_dpp(0, (int)t, 0xB1, 0xf, 0xf, false); if (o1) W[p] = rc; else W[p + 1] = rc; }
; #pragma unroll
	v_mov_b32_e32 v53, s29
	v_pk_add_f32 v[52:53], s[24:25], v[52:53]
	s_nop 0
	v_add_f32_e32 v52, v52, v53
	v_fmamk_f32 v52, v52, 0x3a800000, v29
	v_rsq_f32_e32 v54, v52
	s_nop 0
	v_pk_mul_f32 v[56:57], v[54:55], v[34:35] op_sel_hi:[0,1]
	v_pk_mul_f32 v[164:165], v[6:7], v[56:57]
	v_pk_mul_f32 v[56:57], v[54:55], v[36:37] op_sel_hi:[0,1]
	v_pk_mul_f32 v[166:167], v[8:9], v[56:57]
	v_pk_mul_f32 v[56:57], v[54:55], v[38:39] op_sel_hi:[0,1]
	v_pk_mul_f32 v[168:169], v[2:3], v[56:57]
	v_pk_mul_f32 v[56:57], v[54:55], v[40:41] op_sel_hi:[0,1]
	v_pk_mul_f32 v[170:171], v[4:5], v[56:57]
	v_pk_mul_f32 v[56:57], v[54:55], v[42:43] op_sel_hi:[0,1]
	v_pk_mul_f32 v[172:173], v[14:15], v[56:57]
	v_pk_mul_f32 v[56:57], v[54:55], v[44:45] op_sel_hi:[0,1]
	v_pk_mul_f32 v[174:175], v[16:17], v[56:57]
	v_pk_mul_f32 v[56:57], v[54:55], v[46:47] op_sel_hi:[0,1]
	v_pk_mul_f32 v[176:177], v[10:11], v[56:57]
	v_pk_mul_f32 v[56:57], v[54:55], v[48:49] op_sel_hi:[0,1]
	v_pk_mul_f32 v[178:179], v[12:13], v[56:57]
	v_max3_f32 v58, |v164|, 0, |v165|
	v_max3_f32 v58, v58, |v166|, |v167|
	v_max3_f32 v58, v58, |v168|, |v169|
	v_max3_f32 v58, v58, |v170|, |v171|
	v_max3_f32 v58, v58, |v172|, |v173|
	v_max3_f32 v58, v58, |v174|, |v175|
	v_max3_f32 v58, v58, |v176|, |v177|
	v_max3_f32 v58, v58, |v178|, |v179|
	v_cvt_pk_bf16_f32 v62, v164, v165
	v_cvt_pk_bf16_f32 v63, v166, v167
	v_cvt_pk_bf16_f32 v64, v168, v169
	v_cvt_pk_bf16_f32 v65, v170, v171
	v_cvt_pk_bf16_f32 v66, v172, v173
	v_cvt_pk_bf16_f32 v67, v174, v175
	v_cvt_pk_bf16_f32 v68, v176, v177
	v_cvt_pk_bf16_f32 v69, v178, v179
	buffer_store_dwordx4 v[62:65], v210, s[12:15], 0 offen sc1
	buffer_store_dwordx4 v[66:69], v210, s[12:15], 0 offen offset:1024 sc1
	v_add_u32_e32 v210, 0x4000, v210
	s_nop 1
	v_max_f32_dpp v58, v58, v58 quad_perm:[1,0,3,2] row_mask:0xf bank_mask:0xf
	s_nop 1
	v_max_f32_dpp v58, v58, v58 quad_perm:[2,3,0,1] row_mask:0xf bank_mask:0xf
	s_nop 1
	v_max_f32_dpp v58, v58, v58 row_half_mirror row_mask:0xf bank_mask:0xf
	s_nop 1
	v_max_f32_dpp v58, v58, v58 row_mirror row_mask:0xf bank_mask:0xf
	s_nop 1
	v_readlane_b32 s28, v58, 32
	v_readlane_b32 s29, v58, 48
	v_readlane_b32 s24, v58, 0
	v_readlane_b32 s25, v58, 16
	s_nop 1
	v_mov_b32_e32 v59, s29
	v_max_f32_e32 v59, s28, v59
	v_mov_b32_e32 v70, s25
	v_max3_f32 v59, s24, v70, v59
	v_mul_f32_e32 v70, 0x3c09ae41, v59
	v_cmp_lt_f32_e32 vcc, 0, v59
	s_nop 1
	v_cndmask_b32_e32 v59, 1.0, v70, vcc
	v_div_scale_f32 v70, s[24:25], v59, v59, 1.0
	v_rcp_f32_e32 v71, v70
	v_div_scale_f32 v72, vcc, 1.0, v59, 1.0
	v_fma_f32 v73, -v70, v71, 1.0
	v_fmac_f32_e32 v71, v73, v71
	v_mul_f32_e32 v73, v72, v71
	v_fma_f32 v74, -v70, v73, v72
	v_fmac_f32_e32 v73, v74, v71
	v_fma_f32 v70, -v70, v73, v72
	v_div_fmas_f32 v70, v70, v71, v73
	v_div_fixup_f32 v60, v70, v59, 1.0
	v_pk_mul_f32 v[56:57], v[60:61], v[164:165] op_sel_hi:[0,1]
	v_pk_add_f32 v[180:181], s[46:47], v[56:57]
	v_pk_mul_f32 v[56:57], v[60:61], v[166:167] op_sel_hi:[0,1]
	v_pk_add_f32 v[182:183], s[46:47], v[56:57]
	v_pk_mul_f32 v[56:57], v[60:61], v[168:169] op_sel_hi:[0,1]
	v_pk_add_f32 v[184:185], s[46:47], v[56:57]
	v_pk_mul_f32 v[56:57], v[60:61], v[170:171] op_sel_hi:[0,1]
	v_pk_add_f32 v[186:187], s[46:47], v[56:57]
	v_pk_mul_f32 v[56:57], v[60:61], v[172:173] op_sel_hi:[0,1]
	v_pk_add_f32 v[188:189], s[46:47], v[56:57]
	v_pk_mul_f32 v[56:57], v[60:61], v[174:175] op_sel_hi:[0,1]
	v_pk_add_f32 v[190:191], s[46:47], v[56:57]
	v_pk_mul_f32 v[56:57], v[60:61], v[176:177] op_sel_hi:[0,1]
	v_pk_add_f32 v[192:193], s[46:47], v[56:57]
	v_pk_mul_f32 v[56:57], v[60:61], v[178:179] op_sel_hi:[0,1]
	v_pk_add_f32 v[194:195], s[46:47], v[56:57]
	v_add3_u32 v208, v180, v181, v182
	v_add3_u32 v208, v208, v183, v184
	v_add3_u32 v208, v208, v185, v186
	v_add3_u32 v208, v208, v187, v188
	v_add3_u32 v208, v208, v189, v190
	v_add3_u32 v208, v208, v191, v192
	v_add3_u32 v208, v208, v193, v194
	v_add_u32_e32 v208, v208, v195
	v_add_u32_e32 v208, 0x4bffff80, v208
	v_perm_b32 v204, v182, v180, s48
	v_perm_b32 v205, v186, v184, s48
	v_perm_b32 v196, v205, v204, s49
	v_perm_b32 v204, v183, v181, s48
	v_perm_b32 v205, v187, v185, s48
	v_perm_b32 v197, v205, v204, s49
	v_lshlrev_b32_e32 v204, 4, v197
	v_lshrrev_b32_e32 v205, 4, v196
	v_bfi_b32 v202, s45, v196, v204
	v_bfi_b32 v200, s45, v205, v197
	v_xor_b32_e32 v202, 0x88888888, v202
	v_perm_b32 v204, v190, v188, s48
	v_perm_b32 v205, v194, v192, s48
	v_perm_b32 v196, v205, v204, s49
	v_perm_b32 v204, v191, v189, s48
	v_perm_b32 v205, v195, v193, s48
	v_perm_b32 v197, v205, v204, s49
	v_lshlrev_b32_e32 v204, 4, v197
	v_lshrrev_b32_e32 v205, 4, v196
	v_bfi_b32 v203, s45, v196, v204
	v_bfi_b32 v201, s45, v205, v197
	v_xor_b32_e32 v203, 0x88888888, v203
	v_cndmask_b32_e64 v204, v200, v201, s[4:5]
	v_cndmask_b32_e64 v205, v202, v203, s[4:5]
	s_nop 1
	v_mov_b32_dpp v206, v204 quad_perm:[1,0,3,2] row_mask:0xf bank_mask:0xf
	v_mov_b32_dpp v207, v205 quad_perm:[1,0,3,2] row_mask:0xf bank_mask:0xf
	s_nop 0
	v_cndmask_b32_e64 v200, v206, v200, s[4:5]
	v_cndmask_b32_e64 v201, v201, v206, s[4:5]
	v_cndmask_b32_e64 v202, v207, v202, s[4:5]
	v_cndmask_b32_e64 v203, v203, v207, s[4:5]
	v_cndmask_b32_e64 v204, v200, v202, s[6:7]
	v_cndmask_b32_e64 v205, v201, v203, s[6:7]
	s_nop 1
	v_mov_b32_dpp v206, v204 quad_perm:[2,3,0,1] row_mask:0xf bank_mask:0xf
	v_mov_b32_dpp v207, v205 quad_perm:[2,3,0,1] row_mask:0xf bank_mask:0xf
	s_nop 0
	v_cndmask_b32_e64 v200, v206, v200, s[6:7]
	v_cndmask_b32_e64 v202, v202, v206, s[6:7]
	v_cndmask_b32_e64 v201, v207, v201, s[6:7]
	v_cndmask_b32_e64 v203, v203, v207, s[6:7]
	buffer_store_dwordx4 v[200:203], v211, s[16:19], 0 offen sc1
	v_add_u32_e32 v211, 0x1000, v211
	s_nop 1
	v_add_u32_dpp v208, v208, v208 quad_perm:[1,0,3,2] row_mask:0xf bank_mask:0xf bound_ctrl:1
	s_nop 1
	v_add_u32_dpp v208, v208, v208 quad_perm:[2,3,0,1] row_mask:0xf bank_mask:0xf bound_ctrl:1
	s_nop 1
	v_add_u32_dpp v208, v208, v208 row_half_mirror row_mask:0xf bank_mask:0xf bound_ctrl:1
	s_nop 1
	v_add_u32_dpp v208, v208, v208 row_mirror row_mask:0xf bank_mask:0xf bound_ctrl:1
	s_nop 1
	v_readlane_b32 s28, v208, 0
	v_readlane_b32 s29, v208, 16
	v_readlane_b32 s30, v208, 32
	v_readlane_b32 s31, v208, 48
	s_nop 1
	s_add_i32 s28, s29, s28
	s_add_i32 s28, s28, s30
	s_add_i32 s30, s28, s31
	s_and_saveexec_b64 s[24:25], s[8:9]
	global_store_dword v30, v59, s[98:99] sc1
	v_mov_b32_e32 v70, s30
	global_store_dword v31, v70, s[98:99] sc1
	s_mov_b64 exec, s[24:25]
	s_add_u32 s98, s98, 32
	s_addc_u32 s99, s99, 0
	s_add_i32 s32, s32, 1
	s_cmp_eq_u32 s32, 3
	s_cselect_b32 s100, 0, s100
	s_cmp_lg_u32 s32, 4
	s_cbranch_scc1 .Lp8_trip
